# mLSTM: gate prefix sum with DPP instead of six ds_bpermute round trips; state-update phase hand-scheduled (Kw fragment read once, V fragments one tile ahead, counted lgkmcnt)
# speedup vs baseline: 1.0205x; 1.0062x over previous
; #define LAS __attribute__((address_space(3)))
; __device__ __forceinline__ float bf2f(bf16_t b) { return __uint_as_float(((unsigned)b) << 16); }
; __device__ __forceinline__ float softplusf_(float x) { return fmaxf(x, 0.f) + log1pf(__expf(-fabsf(x))); }
; __device__ __forceinline__ void ml_block(KP p, int e, int b, int hd, int half, LAS unsigned char* lds, const bf16_t* P, bf16_t* YB) {
;     ...
;     auto gates = [&](LAS float* GB) {
;         const float ipv = bf2f(gi_r) + ibias;
;         const float f = bf2f(gf_r) + fbias;
;         float lf = -softplusf_(-f);
; #pragma unroll
;         for (int o = 1; o < 64; o <<= 1) { const float t = __shfl_up(lf, o); if (lane >= o) lf += t; }
;         GB[lane] = lf; GB[64 + lane] = ipv;
;     };
.LBB0_359:
	s_or_b64 exec, exec, s[46:47]
	s_and_b64 s[78:79], s[10:11], s[42:43]
	ds_write_b16 v176, v42 offset:35248
	s_and_saveexec_b64 s[46:47], s[78:79]
	s_cbranch_execz .LBB0_362
	v_lshlrev_b32_e32 v42, 16, v124
	v_add_f32_e32 v42, v112, v42
	v_max_f32_e64 v44, -v42, 0
	v_mul_f32_e64 v42, |v42|, s68
	v_exp_f32_e32 v45, v42
	s_mov_b32 s2, 0x3f2aaaab
	s_and_b64 s[44:45], s[44:45], exec
	s_mov_b32 s33, 0x1f600
	v_add_f32_e32 v46, 1.0, v45
	v_add_f32_e32 v42, -1.0, v46
	v_sub_f32_e32 v43, v42, v46
	v_add_f32_e32 v43, 1.0, v43
	v_sub_f32_e32 v42, v45, v42
	v_add_f32_e32 v47, v42, v43
	v_frexp_mant_f32_e32 v42, v46
	v_cmp_gt_f32_e32 vcc, s2, v42
	v_cvt_f64_f32_e32 v[42:43], v46
	v_frexp_exp_i32_f64_e32 v42, v[42:43]
	v_subbrev_co_u32_e32 v42, vcc, 0, v42, vcc
	v_sub_u32_e32 v43, 0, v42
	v_ldexp_f32 v46, v46, v43
	v_ldexp_f32 v43, v47, v43
	v_add_f32_e32 v47, -1.0, v46
	v_add_f32_e32 v48, 1.0, v47
	v_sub_f32_e32 v48, v46, v48
	v_add_f32_e32 v48, v43, v48
	v_add_f32_e32 v49, v47, v48
	v_sub_f32_e32 v47, v49, v47
	v_sub_f32_e32 v47, v48, v47
	v_add_f32_e32 v48, 1.0, v46
	v_add_f32_e32 v50, -1.0, v48
	v_sub_f32_e32 v46, v46, v50
	v_add_f32_e32 v43, v43, v46
	v_add_f32_e32 v46, v48, v43
	v_sub_f32_e32 v48, v46, v48
	v_sub_f32_e32 v43, v43, v48
	v_rcp_f32_e32 v48, v46
	v_cvt_f32_i32_e32 v42, v42
	s_mov_b32 s2, 0x3f317218
	v_cmp_neq_f32_e32 vcc, s89, v45
	v_mul_f32_e32 v50, v49, v48
	v_mul_f32_e32 v51, v46, v50
	v_fma_f32 v52, v50, v46, -v51
	v_fmac_f32_e32 v52, v50, v43
	v_add_f32_e32 v53, v51, v52
	v_sub_f32_e32 v54, v49, v53
	v_sub_f32_e32 v49, v49, v54
	v_sub_f32_e32 v51, v53, v51
	v_sub_f32_e32 v49, v49, v53
	v_add_f32_e32 v47, v47, v49
	v_sub_f32_e32 v49, v51, v52
	v_add_f32_e32 v47, v49, v47
	v_add_f32_e32 v49, v54, v47
	v_mul_f32_e32 v51, v48, v49
	v_mul_f32_e32 v52, v46, v51
	v_fma_f32 v46, v51, v46, -v52
	v_fmac_f32_e32 v46, v51, v43
	v_sub_f32_e32 v43, v54, v49
	v_add_f32_e32 v43, v47, v43
	v_add_f32_e32 v47, v52, v46
	v_sub_f32_e32 v53, v49, v47
	v_sub_f32_e32 v49, v49, v53
	v_sub_f32_e32 v52, v47, v52
	v_sub_f32_e32 v47, v49, v47
	v_add_f32_e32 v43, v43, v47
	v_sub_f32_e32 v46, v52, v46
	v_add_f32_e32 v43, v46, v43
	v_add_f32_e32 v46, v50, v51
	v_add_f32_e32 v43, v53, v43
	v_sub_f32_e32 v47, v46, v50
	v_mul_f32_e32 v43, v48, v43
	v_sub_f32_e32 v47, v51, v47
	v_add_f32_e32 v43, v47, v43
	v_mul_f32_e32 v50, 0x3f317218, v42
	v_add_f32_e32 v47, v46, v43
	v_fma_f32 v51, v42, s2, -v50
	v_mul_f32_e32 v48, v47, v47
	v_fmac_f32_e32 v51, 0xb102e308, v42
	v_sub_f32_e32 v42, v47, v46
	v_fmamk_f32 v49, v48, 0x3e9b6dac, v235
	v_sub_f32_e32 v42, v43, v42
	v_add_f32_e32 v43, v50, v51
	v_fmaak_f32 v49, v48, v49, 0x3f2aaada
	v_sub_f32_e32 v46, v43, v50
	v_ldexp_f32 v50, v47, 1
	v_mul_f32_e32 v47, v47, v48
	v_mul_f32_e32 v47, v47, v49
	v_add_f32_e32 v48, v50, v47
	v_sub_f32_e32 v49, v48, v50
	v_ldexp_f32 v42, v42, 1
	v_sub_f32_e32 v47, v47, v49
	v_add_f32_e32 v42, v42, v47
	v_add_f32_e32 v47, v48, v42
	v_sub_f32_e32 v48, v47, v48
	v_sub_f32_e32 v42, v42, v48
	v_add_f32_e32 v48, v43, v47
	v_sub_f32_e32 v49, v48, v43
	v_sub_f32_e32 v50, v48, v49
	v_sub_f32_e32 v46, v51, v46
	v_sub_f32_e32 v43, v43, v50
	v_sub_f32_e32 v47, v47, v49
	v_add_f32_e32 v43, v47, v43
	v_add_f32_e32 v47, v46, v42
	v_sub_f32_e32 v49, v47, v46
	v_sub_f32_e32 v50, v47, v49
	v_sub_f32_e32 v46, v46, v50
	v_sub_f32_e32 v42, v42, v49
	v_add_f32_e32 v43, v47, v43
	v_add_f32_e32 v42, v42, v46
	v_add_f32_e32 v46, v48, v43
	v_sub_f32_e32 v47, v46, v48
	v_sub_f32_e32 v43, v43, v47
	v_add_f32_e32 v42, v42, v43
	v_add_f32_e32 v42, v46, v42
	v_cndmask_b32_e32 v42, v245, v42, vcc
	v_cmp_ngt_f32_e32 vcc, -1.0, v45
	s_mov_b32 s2, 0x33800000
	s_cselect_b32 s33, s33, 0x1de00
	v_cndmask_b32_e32 v42, v246, v42, vcc
	v_cmp_neq_f32_e32 vcc, -1.0, v45
	s_add_i32 s33, s33, 0
	s_cmp_gt_u32 s53, 61
	v_cndmask_b32_e32 v42, v247, v42, vcc
	v_cmp_lt_f32_e64 vcc, |v45|, s2
	s_nop 1
	v_cndmask_b32_e32 v42, v42, v45, vcc
	v_add_f32_e32 v42, v44, v42
	v_lshl_add_u32 v44, v130, 2, s33
	v_xor_b32_e32 v42, 0x80000000, v42
	s_nop 1
	v_add_f32_dpp v42, v42, v42 row_shr:1 row_mask:0xf bank_mask:0xf
	s_nop 1
	v_add_f32_dpp v42, v42, v42 row_shr:2 row_mask:0xf bank_mask:0xf
	s_nop 1
	v_add_f32_dpp v42, v42, v42 row_shr:4 row_mask:0xf bank_mask:0xf
	s_nop 1
	v_add_f32_dpp v42, v42, v42 row_shr:8 row_mask:0xf bank_mask:0xf
	s_nop 1
	v_add_f32_dpp v42, v42, v42 row_bcast:15 row_mask:0xa bank_mask:0xf
	s_nop 1
	v_add_f32_dpp v42, v42, v42 row_bcast:31 row_mask:0xc bank_mask:0xf
	v_lshlrev_b32_e32 v43, 16, v114
	v_add_f32_e32 v43, v89, v43
	ds_write2st64_b32 v44, v42, v43 offset1:1
	s_cbranch_scc1 .LBB0_362
	v_lshl_add_u64 v[42:43], s[50:51], 0, v[98:99]
	v_add_co_u32_e32 v42, vcc, 0x126d1000, v42
	s_nop 1
	v_addc_co_u32_e32 v43, vcc, 0, v43, vcc
	global_load_ushort v114, v[42:43], off offset:2048
	global_load_ushort v124, v[42:43], off offset:2056

; #define LAS __attribute__((address_space(3)))
; __device__ __forceinline__ unsigned pk2(float lo, float hi) { const f32x2 v = {lo, hi}; const bf16x2n b = __builtin_convertvector(v, bf16x2n); return __builtin_bit_cast(unsigned, b); }
; __device__ __forceinline__ f32x4 mfma16(bf16x8 a, bf16x8 b, f32x4 c) { return __builtin_amdgcn_mfma_f32_16x16x32_bf16(a, b, c, 0, 0, 0); }
; #define LDS_BAR() do { asm volatile("s_waitcnt lgkmcnt(0)" ::: "memory"); __builtin_amdgcn_s_barrier(); asm volatile("" ::: "memory"); } while (0)
; __device__ __forceinline__ void ml_block(KP p, int e, int b, int hd, int half, LAS unsigned char* lds, const bf16_t* P, bf16_t* YB) {
;     ...
;                     for (int jj = 0; jj < 4; ++jj) ot[q][jj] = a1[jj] + __expf(Bc[oit * 16 + fq * 4 + jj]) * a2[jj];
;                 }
;             }
;         }
;         const float decay = __expf(Bc[63]);
;         LDS_BAR();
;         {
; #pragma unroll
;             for (int et = 0; et < 9; ++et) {
;                 f32x4 acc = st[et] * decay;
; #pragma unroll
;                 for (int kb = 0; kb < 2; ++kb) {
;                     const bf16x8 af = *(const LAS bf16x8*)(KwT + (wid * 16 + fr) * 72 + kb * 32 + fq * 8);
;                     const bf16x8 bf = *(const LAS bf16x8*)(VT + (et * 16 + fr) * 72 + kb * 32 + fq * 8);
;                     acc = mfma16(af, bf, acc);
;                 }
;                 st[et] = acc;
;                 u32x2 w; w.x = pk2(acc[0], acc[1]); w.y = pk2(acc[2], acc[3]);
;                 *(LAS u32x2*)(CT + (et * 16 + fr) * 136 + wid * 16 + fq * 4) = w;
;             }
; #pragma unroll
;             for (int q = 0; q < 3; ++q) if (q < onet) {
; #pragma unroll
;                 for (int jj = 0; jj < 4; ++jj) Of[(oit * 16 + fq * 4 + jj) * 148 + (oet0 + q) * 16 + fr] = ot[q][jj];
;             }
.LBB0_364:
	s_or_b64 exec, exec, s[44:45]
	v_fma_f32 v50, v50, v108, v42
	v_mov_b32_e32 v42, s7
	ds_read_b32 v42, v42
	s_waitcnt lgkmcnt(0)
	s_barrier
	v_fma_f32 v51, v51, v109, v43
	s_waitcnt lgkmcnt(0)
	v_mul_f32_e32 v42, 0x3fb8aa3b, v42
	v_fma_f32 v43, v52, v110, v44
	v_fmac_f32_e32 v45, v53, v111
	v_exp_f32_e32 v42, v42
	ds_read_b128 v[212:215], v90 offset:44032
	ds_read_b128 v[216:219], v90 offset:44096
	ds_read_b128 v[52:55], v170 offset:62464
	ds_read_b128 v[56:59], v170 offset:62528
	v_fma_f32 v44, v110, v80, v48
	v_add_u32_e32 v48, v91, v165
	v_fma_f32 v46, v108, v78, v46
	v_fma_f32 v47, v109, v79, v47
	v_fmac_f32_e32 v49, v111, v81
	v_pk_mul_f32 v[8:9], v[8:9], v[42:43] op_sel_hi:[1,0]
	v_pk_mul_f32 v[6:7], v[6:7], v[42:43] op_sel_hi:[1,0]
	v_pk_mul_f32 v[12:13], v[12:13], v[42:43] op_sel_hi:[1,0]
	v_pk_mul_f32 v[10:11], v[10:11], v[42:43] op_sel_hi:[1,0]
	v_pk_mul_f32 v[16:17], v[16:17], v[42:43] op_sel_hi:[1,0]
	v_pk_mul_f32 v[14:15], v[14:15], v[42:43] op_sel_hi:[1,0]
	v_mul_f32_e64 v20, v20, v42
	v_mul_f32_e64 v21, v21, v42
	v_pk_mul_f32 v[18:19], v[18:19], v[42:43] op_sel_hi:[1,0]
	v_pk_mul_f32 v[24:25], v[24:25], v[42:43] op_sel_hi:[1,0]
	v_pk_mul_f32 v[22:23], v[22:23], v[42:43] op_sel_hi:[1,0]
	v_pk_mul_f32 v[28:29], v[28:29], v[42:43] op_sel_hi:[1,0]
	v_mul_f32_e64 v26, v26, v42
	v_mul_f32_e64 v27, v27, v42
	v_pk_mul_f32 v[32:33], v[32:33], v[42:43] op_sel_hi:[1,0]
	v_pk_mul_f32 v[30:31], v[30:31], v[42:43] op_sel_hi:[1,0]
	v_pk_mul_f32 v[36:37], v[36:37], v[42:43] op_sel_hi:[1,0]
	v_pk_mul_f32 v[34:35], v[34:35], v[42:43] op_sel_hi:[1,0]
	v_mul_f32_e64 v40, v40, v42
	v_mul_f32_e64 v41, v41, v42
	v_pk_mul_f32 v[38:39], v[38:39], v[42:43] op_sel_hi:[1,0]
	v_add_u32_e32 v42, 0x400, v175
	ds_read_b128 v[220:223], v170 offset:64768
	ds_read_b128 v[228:231], v170 offset:64832
	s_waitcnt lgkmcnt(2)
	v_mfma_f32_16x16x32_bf16 v[6:9], v[212:215], v[52:55], v[6:9]
	v_mfma_f32_16x16x32_bf16 v[6:9], v[216:219], v[56:59], v[6:9]
	ds_read_b128 v[52:55], v177 offset:62464
	ds_read_b128 v[56:59], v177 offset:62528
	s_waitcnt lgkmcnt(2)
	v_mfma_f32_16x16x32_bf16 v[10:13], v[212:215], v[220:223], v[10:13]
	v_mfma_f32_16x16x32_bf16 v[10:13], v[216:219], v[228:231], v[10:13]
	s_nop 2
	v_cvt_pk_bf16_f32 v224, v6, v7
	v_cvt_pk_bf16_f32 v225, v8, v9
	ds_write_b64 v171, v[224:225]
	ds_read_b128 v[220:223], v172 offset:62464
	ds_read_b128 v[228:231], v172 offset:62528
	s_waitcnt lgkmcnt(3)
	v_mfma_f32_16x16x32_bf16 v[14:17], v[212:215], v[52:55], v[14:17]
	v_mfma_f32_16x16x32_bf16 v[14:17], v[216:219], v[56:59], v[14:17]
	v_cvt_pk_bf16_f32 v232, v10, v11
	v_cvt_pk_bf16_f32 v233, v12, v13
	ds_write_b64 v171, v[232:233] offset:4352
	ds_read_b128 v[52:55], v172 offset:64768
	ds_read_b128 v[56:59], v172 offset:64832
	s_waitcnt lgkmcnt(3)
	v_mfma_f32_16x16x32_bf16 v[18:21], v[212:215], v[220:223], v[18:21]
	v_mfma_f32_16x16x32_bf16 v[18:21], v[216:219], v[228:231], v[18:21]
	v_cvt_pk_bf16_f32 v224, v14, v15
	v_cvt_pk_bf16_f32 v225, v16, v17
	ds_write_b64 v48, v[224:225]
	ds_read_b128 v[220:223], v173 offset:62464
	ds_read_b128 v[228:231], v173 offset:62528
	s_waitcnt lgkmcnt(3)
	v_mfma_f32_16x16x32_bf16 v[22:25], v[212:215], v[52:55], v[22:25]
	v_mfma_f32_16x16x32_bf16 v[22:25], v[216:219], v[56:59], v[22:25]
	v_cvt_pk_bf16_f32 v232, v18, v19
	v_cvt_pk_bf16_f32 v233, v20, v21
	ds_write_b64 v171, v[232:233] offset:13056
	ds_read_b128 v[52:55], v173 offset:64768
	ds_read_b128 v[56:59], v173 offset:64832
	s_waitcnt lgkmcnt(3)
	v_mfma_f32_16x16x32_bf16 v[26:29], v[212:215], v[220:223], v[26:29]
	v_mfma_f32_16x16x32_bf16 v[26:29], v[216:219], v[228:231], v[26:29]
	v_cvt_pk_bf16_f32 v224, v22, v23
	v_cvt_pk_bf16_f32 v225, v24, v25
	ds_write_b64 v171, v[224:225] offset:17408
	ds_read_b128 v[220:223], v174 offset:62464
	ds_read_b128 v[228:231], v174 offset:62528
	s_waitcnt lgkmcnt(3)
	v_mfma_f32_16x16x32_bf16 v[30:33], v[212:215], v[52:55], v[30:33]
	v_mfma_f32_16x16x32_bf16 v[30:33], v[216:219], v[56:59], v[30:33]
	v_cvt_pk_bf16_f32 v232, v26, v27
	v_cvt_pk_bf16_f32 v233, v28, v29
	ds_write_b64 v171, v[232:233] offset:21760
	ds_read_b128 v[52:55], v174 offset:64768
	ds_read_b128 v[56:59], v174 offset:64832
	s_waitcnt lgkmcnt(3)
	v_mfma_f32_16x16x32_bf16 v[34:37], v[212:215], v[220:223], v[34:37]
	v_mfma_f32_16x16x32_bf16 v[34:37], v[216:219], v[228:231], v[34:37]
	v_cvt_pk_bf16_f32 v224, v30, v31
	v_cvt_pk_bf16_f32 v225, v32, v33
	ds_write_b64 v171, v[224:225] offset:26112
	s_waitcnt lgkmcnt(1)
	v_mfma_f32_16x16x32_bf16 v[38:41], v[212:215], v[52:55], v[38:41]
	v_mfma_f32_16x16x32_bf16 v[38:41], v[216:219], v[56:59], v[38:41]
	s_nop 1
	v_cvt_pk_bf16_f32 v232, v34, v35
	v_cvt_pk_bf16_f32 v233, v36, v37
	ds_write_b64 v171, v[232:233] offset:30464
	s_nop 7
	v_cvt_pk_bf16_f32 v224, v38, v39
	v_cvt_pk_bf16_f32 v225, v40, v41
	ds_write_b64 v171, v[224:225] offset:34816
	ds_write2_b32 v175, v50, v46 offset1:16
	ds_write2_b32 v175, v51, v47 offset0:148 offset1:164
	ds_write2_b32 v42, v43, v44 offset0:40 offset1:56
	ds_write2_b32 v42, v45, v49 offset0:188 offset1:204
	s_and_saveexec_b64 s[44:45], s[24:25]
	s_cbranch_execz .LBB0_366
	v_add_u32_e32 v42, v148, v166
	ds_write2_b32 v42, v106, v107 offset0:32 offset1:180
	v_add_u32_e32 v42, 0x400, v42
	ds_write2_b32 v42, v104, v105 offset0:72 offset1:220
